# scan: K=16 MFMA opcode in chunk chain + loop-invariant hoisting; helpers: 12 base units each, sample tail after 2nd sub-barrier
# speedup vs baseline: 1.0097x; 1.0097x over previous
.LBB0_537:
	s_or_b64 exec, exec, s[0:1]
	s_and_b64 s[0:1], s[36:37], exec
	s_cselect_b32 s28, 16, 0x1000
	s_add_u32 s64, s76, 0x13d00000
	s_addc_u32 s65, s77, 0
	s_bfe_u32 s68, s96, 0x20006
	s_mul_i32 s0, s68, 0x3700
	s_add_i32 s71, s0, 0
	s_and_b32 s0, s96, 0xffffff00
	s_lshr_b32 s74, s96, 8
	s_add_i32 s84, s0, 0
	s_lshl_b32 s11, s74, 5
	s_add_i32 s80, s84, 0x12600
	s_cmpk_lt_u32 s96, 0x540
	v_readlane_b32 s20, v255, 31
	s_cselect_b64 s[40:41], -1, 0
	s_add_i32 s12, s20, -4
	s_lshl_b32 s13, s12, 2
	s_lshl_b32 s22, s12, 10
	s_cmpk_lt_u32 s96, 0x440
	s_cselect_b64 s[42:43], -1, 0
	s_lshl_b32 s66, s20, 10
	s_cmpk_lt_u32 s96, 0x340
	s_cselect_b64 s[46:47], -1, 0
	s_add_i32 s14, s20, 4
	s_lshl_b32 s15, s14, 2
	s_lshl_b32 s23, s14, 10
	s_cmpk_lt_u32 s96, 0x240
	s_cselect_b64 s[48:49], -1, 0
	s_add_i32 s16, s20, 8
	s_lshl_b32 s17, s16, 2
	s_lshl_b32 s24, s16, 10
	s_cmp_eq_u32 s20, 4
	s_cselect_b64 s[50:51], -1, 0
	s_cmp_eq_u32 s20, 2
	s_mov_b32 s0, 0xfc00000
	s_cselect_b32 s38, s0, 0x13d00000
	s_add_u32 s8, s76, s6
	s_addc_u32 s9, s77, 0
	s_mul_i32 s0, s20, 0x2400
	s_add_i32 s1, 0, 0x1a900
	s_add_i32 s81, s1, s0
	s_lshl_b32 s0, s74, 7
	s_add_i32 s83, s0, 0
	s_add_i32 s82, s81, 0x2000
	s_add_i32 s83, s83, 0x14800
	s_add_i32 s84, s84, 0x12400
	s_lshl_b32 s29, s20, 5
	s_add_u32 s6, s64, s6
	s_addc_u32 s7, s65, 0
	s_lshl_b32 s85, s33, 10
	s_add_u32 s18, s76, 0x10000
	v_writelane_b32 v255, s96, 33
	s_addc_u32 s19, s77, 0
	v_lshl_or_b32 v11, s68, 4, v9
	v_writelane_b32 v255, s18, 34
	v_add_u32_e32 v25, 1, v11
	v_lshlrev_b32_e32 v27, 3, v38
	v_writelane_b32 v255, s19, 35
	v_lshlrev_b32_e32 v10, 7, v25
	v_and_b32_e32 v22, 8, v27
	s_add_i32 s0, 0, 0x1cd00
	s_add_i32 s18, 0, 0x1f100
	v_add3_u32 v91, s1, v10, v22
	v_add3_u32 v92, s0, v10, v22
	v_add3_u32 v93, s18, v10, v22
	v_lshlrev_b32_e32 v10, 8, v25
	s_add_i32 s19, 0, 0x23900
	v_add3_u32 v28, s19, v10, v22
	v_lshlrev_b32_e32 v10, 7, v11
	v_add3_u32 v94, s1, v10, v22
	v_add3_u32 v95, s0, v10, v22
	v_add3_u32 v96, s18, v10, v22
	v_lshlrev_b32_e32 v10, 8, v11
	v_add3_u32 v29, s19, v10, v22
	v_add_u32_e32 v10, 1, v89
	s_add_i32 s19, 0, 0x21500
	v_lshl_add_u32 v32, v10, 7, s19
	v_xor_b32_e32 v10, v10, v39
	v_lshlrev_b32_e32 v10, 4, v10
	v_and_b32_e32 v33, 0x70, v10
	v_lshlrev_b32_e32 v10, 7, v89
	v_add_u32_e32 v34, s19, v10
	s_add_i32 s19, 0, 0x12800
	s_cmp_lg_u32 s12, 16
	v_add_u32_e32 v36, s19, v10
	v_or_b32_e32 v10, s13, v38
	s_cselect_b64 vcc, -1, 0
	v_xor_b32_e32 v22, v89, v39
	v_cndmask_b32_e32 v98, 64, v10, vcc
	v_bitop3_b32 v10, v38, v39, s13 bitop3:0x36
	v_lshlrev_b32_e32 v22, 4, v22
	v_and_or_b32 v10, v10, 7, v41
	v_and_b32_e32 v35, 0x70, v22
	v_lshlrev_b32_e32 v22, 4, v10
	v_mov_b32_e32 v10, 0
	v_mov_b32_e32 v23, v10
	s_cmp_lg_u32 s20, 16
	v_lshl_add_u64 v[48:49], s[4:5], 0, v[22:23]
	v_or_b32_e32 v22, s3, v38
	s_cselect_b64 vcc, -1, 0
	v_cndmask_b32_e32 v99, 64, v22, vcc
	v_bitop3_b32 v22, v38, v39, s3 bitop3:0x36
	v_and_or_b32 v22, v22, 7, v41
	v_lshlrev_b32_e32 v22, 4, v22
	s_cmp_lg_u32 s14, 16
	v_lshl_add_u64 v[50:51], s[4:5], 0, v[22:23]
	v_or_b32_e32 v22, s15, v38
	s_cselect_b64 vcc, -1, 0
	v_cndmask_b32_e32 v100, 64, v22, vcc
	v_bitop3_b32 v22, v38, v39, s15 bitop3:0x36
	v_and_or_b32 v22, v22, 7, v41
	v_lshlrev_b32_e32 v22, 4, v22
	s_cmp_lg_u32 s16, 16
	v_lshl_add_u64 v[52:53], s[4:5], 0, v[22:23]
	v_or_b32_e32 v22, s17, v38
	s_cselect_b64 vcc, -1, 0
	v_cndmask_b32_e32 v101, 64, v22, vcc
	v_bitop3_b32 v22, v38, v39, s17 bitop3:0x36
	v_and_or_b32 v22, v22, 7, v41
	v_lshlrev_b32_e32 v22, 4, v22
	v_lshl_add_u64 v[54:55], s[4:5], 0, v[22:23]
	v_xor_b32_e32 v22, v38, v20
	s_movk_i32 s10, 0x3700
	v_or_b32_e32 v22, v22, v41
	v_lshlrev_b32_e32 v41, 5, v9
	v_lshrrev_b32_e32 v45, 7, v42
	v_cmp_gt_u32_e64 s[0:1], 16, v40
	v_or_b32_e32 v103, v27, v41
	v_lshl_add_u32 v104, v40, 2, s71
	v_add_u32_e32 v40, s71, v41
	v_lshrrev_b32_e32 v41, 2, v9
	v_mul_lo_u32 v45, v45, s10
	v_or_b32_e32 v41, v90, v41
	v_add_u32_e32 v67, 0, v45
	v_bfe_u32 v45, v42, 3, 4
	v_mul_u32_u24_e32 v41, 0x48, v41
	v_and_b32_e32 v21, 12, v21
	v_mul_u32_u24_e32 v45, 0x48, v45
	v_or_b32_e32 v24, s11, v90
	v_add_lshl_u32 v105, v21, v41, 1
	v_lshl_or_b32 v21, v89, 6, v8
	v_add_lshl_u32 v8, v45, v8, 1
	v_mov_b32_e32 v45, v10
	v_and_b32_e32 v26, 7, v25
	v_lshl_add_u64 v[60:61], s[6:7], 0, v[44:45]
	v_cmp_eq_u32_e64 s[6:7], 0, v42
	v_lshrrev_b32_e32 v42, 3, v24
	v_and_b32_e32 v62, 8, v42
	v_bitop3_b32 v63, v42, v26, 5 bitop3:0x6c
	v_or_b32_e32 v63, v63, v62
	v_lshlrev_b32_e32 v68, 4, v63
	v_add_u32_e32 v63, 64, v24
	v_bitop3_b32 v45, v42, v25, 7 bitop3:0x78
	v_lshrrev_b32_e32 v64, 3, v63
	v_xor_b32_e32 v69, v42, v20
	v_bitop3_b32 v42, v42, v20, 5 bitop3:0x6c
	v_and_b32_e32 v65, 8, v64
	v_or_b32_e32 v42, v42, v62
	v_bitop3_b32 v62, v64, v20, 5 bitop3:0x6c
	v_or_b32_e32 v62, v62, v65
	v_lshlrev_b32_e32 v108, 4, v69
	v_lshlrev_b32_e32 v69, 4, v62
	v_or_b32_e32 v62, 16, v24
	v_lshlrev_b32_e32 v22, 4, v22
	v_lshlrev_b32_e32 v71, 1, v63
	v_lshrrev_b32_e32 v63, 3, v62
	v_lshl_add_u64 v[56:57], s[4:5], 0, v[22:23]
	v_xor_b32_e32 v22, v88, v20
	v_bitop3_b32 v26, v64, v26, 5 bitop3:0x6c
	v_bitop3_b32 v64, v63, v25, 7 bitop3:0x78
	v_lshlrev_b32_e32 v22, 4, v22
	v_or_b32_e32 v26, v26, v65
	v_lshlrev_b32_e32 v111, 4, v64
	v_and_b32_e32 v64, 8, v63
	v_bitop3_b32 v65, v63, v25, 7 bitop3:0x28
	s_movk_i32 s18, 0x48
	v_lshl_add_u64 v[58:59], s[8:9], 0, v[22:23]
	v_or_b32_e32 v23, s11, v9
	v_or_b32_e32 v65, v65, v64
	v_mul_u32_u24_e32 v30, 0x48, v11
	v_mul_u32_u24_e32 v31, 0x48, v9
	v_lshlrev_b32_e32 v97, 2, v11
	v_or_b32_e32 v22, 16, v90
	v_lshlrev_b32_e32 v72, 4, v65
	v_add_u32_e32 v65, 0x50, v24
	v_mul_lo_u32 v23, v23, s18
	v_mad_u32_u24 v11, v11, s18, 32
	v_lshlrev_b32_e32 v70, 1, v24
	v_add_lshl_u32 v109, v24, v30, 1
	v_add_lshl_u32 v110, v24, v31, 1
	v_lshrrev_b32_e32 v73, 3, v65
	v_xor_b32_e32 v75, v63, v20
	v_bitop3_b32 v63, v63, v20, 7 bitop3:0x6c
	v_add_lshl_u32 v113, v62, v30, 1
	v_add_lshl_u32 v115, v30, v90, 1
	v_add_lshl_u32 v116, v22, v30, 1
	v_add_u32_e32 v30, 0x480, v23
	v_add_lshl_u32 v119, v11, v90, 1
	v_add_lshl_u32 v120, v11, v22, 1
	v_or_b32_e32 v11, 32, v90
	v_lshlrev_b32_e32 v123, 2, v24
	v_or_b32_e32 v24, 1, v90
	v_cmp_eq_u32_e32 vcc, v90, v9
	v_lshlrev_b32_e32 v106, 5, v20
	v_and_b32_e32 v74, 8, v73
	v_bitop3_b32 v25, v73, v25, 7 bitop3:0x28
	v_or_b32_e32 v63, v63, v64
	v_bitop3_b32 v20, v73, v20, 7 bitop3:0x6c
	v_lshlrev_b32_e32 v73, 1, v62
	v_add_lshl_u32 v114, v62, v31, 1
	v_add_lshl_u32 v118, v30, v90, 1
	v_add_lshl_u32 v122, v11, v30, 1
	v_lshlrev_b32_e32 v124, 2, v62
	v_or_b32_e32 v30, 2, v90
	v_cndmask_b32_e64 v62, 0, 1.0, vcc
	v_cmp_eq_u32_e32 vcc, v24, v9
	v_lshlrev_b32_e32 v112, 4, v75
	v_lshlrev_b32_e32 v75, 4, v63
	v_add_lshl_u32 v117, v90, v23, 1
	v_add_lshl_u32 v121, v11, v23, 1
	v_add_lshl_u32 v125, v90, v31, 1
	v_add_lshl_u32 v23, v11, v31, 1
	v_or_b32_e32 v31, 3, v90
	v_cndmask_b32_e64 v63, 0, 1.0, vcc
	v_cmp_eq_u32_e32 vcc, v30, v9
	v_cmp_eq_u32_e64 s[4:5], 0, v9
	v_mad_u32_u24 v37, v9, s18, 16
	v_cmp_lt_u32_e64 s[8:9], v90, v9
	v_cmp_gt_u32_e64 s[10:11], v90, v9
	v_cmp_lt_u32_e64 s[12:13], v24, v9
	v_cmp_lt_u32_e64 s[14:15], v30, v9
	v_cmp_gt_u32_e64 s[16:17], v30, v9
	v_cmp_lt_u32_e64 s[18:19], v31, v9
	v_cmp_gt_u32_e64 s[20:21], v31, v9
	v_cndmask_b32_e64 v64, 0, 1.0, vcc
	v_cmp_eq_u32_e32 vcc, v31, v9
	v_lshlrev_b32_e32 v9, 2, v9
	v_lshl_add_u32 v24, v38, 10, s97
	s_mov_b32 s3, 0xdc00
	v_add3_u32 v126, v24, v9, s3
	v_and_b32_e32 v9, 3, v39
	s_movk_i32 s25, 0x2400
	v_lshlrev_b32_e32 v43, 2, v21
	v_lshlrev_b32_e32 v21, 1, v21
	v_lshl_or_b32 v9, v9, 3, s29
	v_lshlrev_b32_e32 v24, 1, v41
	s_waitcnt lgkmcnt(0)
	s_barrier
	v_lshlrev_b32_e32 v66, 2, v89
	v_or_b32_e32 v25, v25, v74
	v_or_b32_e32 v20, v20, v74
	v_add3_u32 v128, v9, v24, s25
	v_mov_b32_e32 v9, 0x3540
	v_add_u32_e32 v151, v67, v8
	v_add_u32_e32 v8, 0, v21
	s_mov_b32 s39, 0
	v_and_b32_e32 v102, 48, v39
	v_lshlrev_b32_e32 v26, 4, v26
	v_lshlrev_b32_e32 v42, 4, v42
	v_lshlrev_b32_e32 v25, 4, v25
	v_lshlrev_b32_e32 v20, 4, v20
	v_lshlrev_b32_e32 v74, 1, v65
	v_add_lshl_u32 v22, v37, v90, 1
	v_add_lshl_u32 v11, v11, v37, 1
	v_writelane_b32 v255, s97, 32
	v_lshl_or_b32 v129, v38, 4, v9
	s_add_i32 s3, 0, 0x15c00
	s_add_i32 s88, s22, 0
	s_add_i32 s89, s23, 0
	s_add_i32 s90, s24, 0
	v_add_u32_e32 v9, 0, v66
	v_add_u32_e32 v152, 0x12800, v8
	v_mbcnt_lo_u32_b32 v8, -1, 0
	s_mov_b64 s[52:53], s[38:39]
	v_add_u32_e32 v107, s70, v89
	v_lshlrev_b32_e32 v45, 4, v45
	v_cndmask_b32_e64 v65, 0, 1.0, vcc
	v_add_u32_e32 v127, 0x2d00, v103
	v_writelane_b32 v255, s29, 44
	v_or_b32_e32 v130, 0x3500, v102
	v_add_u32_e32 v131, v28, v68
	v_add_u32_e32 v132, v28, v26
	v_add_u32_e32 v133, v29, v42
	v_add_u32_e32 v134, v29, v69
	v_add_u32_e32 v135, s3, v70
	v_add_u32_e32 v136, s3, v71
	s_mov_b32 s86, 0x4038aa3b
	s_add_i32 s67, 0, 0x10000
	v_add_u32_e32 v137, v28, v72
	v_add_u32_e32 v138, v28, v25
	v_add_u32_e32 v139, v29, v75
	v_add_u32_e32 v140, v29, v20
	v_add_u32_e32 v141, s3, v73
	v_add_u32_e32 v142, s3, v74
	v_add_u32_e32 v143, v32, v33
	v_add_u32_e32 v145, v34, v35
	s_mov_b32 s87, 0xbfb8aa3b
	v_add_u32_e32 v146, v36, v44
	s_add_i32 s88, s88, 0x23900
	s_add_i32 s89, s89, 0x23900
	s_add_i32 s90, s90, 0x23900
	s_add_i32 s91, 0, 0x27900
	s_add_i32 s92, s81, 0x400
	s_add_i32 s93, s81, 0x800
	s_add_i32 s94, s81, 0xc00
	s_add_i32 s95, s81, 0x1400
	s_add_i32 s96, s81, 0x1800
	s_add_i32 s97, s81, 0x1c00
	s_add_i32 s3, 0, 0x16100
	s_add_i32 s69, 0, 0x18500
	v_mov_b32_e32 v147, 0xbf92477c
	v_add_u32_e32 v148, v40, v27
	s_xor_b64 s[54:55], s[26:27], -1
	v_add_u32_e32 v149, 0, v43
	v_add_u32_e32 v150, 0x12400, v9
	v_mov_b32_e32 v153, 0x3a27c5ac
	v_mbcnt_hi_u32_b32 v144, -1, v8
	v_add_u32_e32 v154, s71, v22
	v_add_u32_e32 v155, s71, v23
	v_add_u32_e32 v156, s71, v11
	s_mov_b32 s33, s28
	s_mov_b32 s29, 0
	v_add_u32_e32 v215, v92, v111
	v_add_u32_e32 v223, s67, v113
	v_add_u32_e32 v218, v96, v112
	v_xor_b32_e32 v243, 32, v144
	v_add_u32_e32 v230, s69, v117
	v_and_b32_e32 v241, 64, v144
	v_or_b32_e32 v240, v102, v241
	v_add_u32_e32 v239, 0x12600, v97
	v_add_u32_e32 v235, s3, v121
	v_add_u32_e32 v237, s3, v122
	v_add_u32_e32 v207, v92, v45
	v_add_u32_e32 v210, v96, v108
	v_add_u32_e32 v211, v93, v45
	v_add_u32_e32 v224, s71, v114
	v_add_u32_e32 v233, s67, v119
	v_xor_b32_e32 v242, 16, v144
	v_add_u32_e32 v21, 64, v241
	v_cmp_lt_i32_e32 vcc, v242, v21
	s_nop 1
	v_cndmask_b32_e32 v20, v144, v242, vcc
	v_lshlrev_b32_e32 v221, 2, v20
	v_add_u32_e32 v217, v95, v112
	v_add_u32_e32 v234, s67, v120
	v_add_u32_e32 v227, s67, v115
	v_add_u32_e32 v220, v91, v111
	v_add_u32_e32 v238, s69, v122
	v_add_u32_e32 v212, v91, v45
	v_cmp_lt_i32_e32 vcc, v243, v21
	s_nop 1
	v_cndmask_b32_e32 v22, v144, v243, vcc
	v_lshlrev_b32_e32 v222, 2, v22
	v_add_u32_e32 v226, s83, v102
	v_add_u32_e32 v236, s69, v121
	v_add_u32_e32 v232, s69, v118
	v_add_u32_e32 v209, v95, v108
	v_add_u32_e32 v214, s71, v110
	v_add_u32_e32 v208, v94, v108
	v_add_u32_e32 v228, s67, v116
	v_add_u32_e32 v229, s3, v117
	v_add_u32_e32 v231, s3, v118
	v_add_u32_e32 v225, 0x15d80, v44
	v_add_u32_e32 v219, v93, v111
	v_add_u32_e32 v213, s67, v109
	v_add_u32_e32 v216, v94, v112
	s_waitcnt vmcnt(0)
.LBB0_538:
	s_sub_i32 s22, s28, s29
	s_min_u32 s24, s22, 64
	s_lshr_b32 s22, s24, 4
	s_cmp_lt_u32 s68, s22
	s_cselect_b64 s[34:35], -1, 0
	s_cmp_ge_u32 s68, s22
	s_cbranch_scc1 .LBB0_542
	ds_read_b64 v[24:25], v207
	ds_read_b64 v[34:35], v132
	ds_read_b64 v[8:9], v208
	ds_read_b64 v[26:27], v209
	ds_read_b64 v[36:37], v210
	ds_read2_b64 v[20:23], v135 offset1:32
	ds_read_b64 v[38:39], v134
	ds_read_b64 v[28:29], v136
	ds_read_b64 v[40:41], v211
	ds_read_b64 v[42:43], v131
	ds_read_b64 v[32:33], v212
	s_waitcnt lgkmcnt(7)
	v_pk_add_f16 v11, v26, v24 neg_lo:[0,1] neg_hi:[0,1]
	v_pk_add_f16 v26, v27, v25 neg_lo:[0,1] neg_hi:[0,1]
	s_waitcnt lgkmcnt(3)
	v_pk_fma_f16 v66, v11, v28, v24
	v_pk_fma_f16 v67, v26, v29, v25
	ds_read_b64 v[68:69], v133
	ds_read2_b64 v[28:31], v135 offset0:96 offset1:112
	s_waitcnt lgkmcnt(4)
	v_pk_add_f16 v11, v36, v40 neg_lo:[0,1] neg_hi:[0,1]
	v_pk_add_f16 v70, v37, v41 neg_lo:[0,1] neg_hi:[0,1]
	v_pk_add_f16 v38, v38, v34 neg_lo:[0,1] neg_hi:[0,1]
	s_waitcnt lgkmcnt(1)
	v_sub_f16_e32 v24, v68, v42
	s_waitcnt lgkmcnt(0)
	v_fma_f16 v24, v24, v28, v42
	v_fma_mix_f32 v24, v24, s86, 0 op_sel_hi:[1,0,0]
	v_lshrrev_b32_e32 v25, 16, v28
	v_exp_f32_e32 v36, v24
	v_lshrrev_b32_e32 v24, 16, v42
	v_sub_f16_sdwa v26, v68, v24 dst_sel:DWORD dst_unused:UNUSED_PAD src0_sel:WORD_1 src1_sel:DWORD
	s_nop 0
	v_fma_f16 v24, v26, v25, v24
	v_fma_mix_f32 v24, v24, s86, 0 op_sel_hi:[1,0,0]
	v_add_f32_e32 v28, 1.0, v36
	v_exp_f32_e32 v37, v24
	v_lshrrev_b32_e32 v42, 16, v43
	ds_read2_b64 v[24:27], v135 offset0:64 offset1:80
	v_rcp_f32_e32 v28, v28
	v_add_f32_e32 v36, 1.0, v37
	v_sub_f16_e32 v37, v69, v43
	v_fma_f16 v37, v37, v29, v43
	v_lshrrev_b32_e32 v29, 16, v29
	v_sub_f16_sdwa v43, v69, v42 dst_sel:DWORD dst_unused:UNUSED_PAD src0_sel:WORD_1 src1_sel:DWORD
	s_nop 0
	v_fma_f16 v29, v43, v29, v42
	v_fma_mix_f32 v37, v37, s86, 0 op_sel_hi:[1,0,0]
	v_fma_mix_f32 v29, v29, s86, 0 op_sel_hi:[1,0,0]
	v_exp_f32_e32 v37, v37
	v_exp_f32_e32 v42, v29
	v_rcp_f32_e32 v29, v36
	s_waitcnt lgkmcnt(0)
	v_pk_mul_f16 v69, v67, v25
	v_add_f32_e32 v36, 1.0, v37
	v_add_f32_e32 v37, 1.0, v42
	v_rcp_f32_e32 v36, v36
	v_rcp_f32_e32 v37, v37
	v_pk_mul_f16 v68, v66, v24
	v_pk_fma_f32 v[24:25], v[28:29], -2.0, 1.0 op_sel_hi:[1,0,0]
	v_pk_add_f16 v39, v39, v35 neg_lo:[0,1] neg_hi:[0,1]
	v_pk_fma_f32 v[28:29], v[36:37], -2.0, 1.0 op_sel_hi:[1,0,0]
	v_pk_fma_f16 v31, v39, v31, v35
	v_cvt_pk_f16_f32 v29, v28, v29
	v_cvt_pk_f16_f32 v28, v24, v25
	v_pk_fma_f16 v30, v38, v30, v34
	ds_write_b64 v109, v[28:29] offset:56320
	v_pk_fma_f16 v23, v70, v23, v41
	v_pk_fma_f16 v22, v11, v22, v40
	ds_write_b64 v213, v[30:31]
	ds_write_b64 v214, v[22:23] offset:9216
	ds_read_b64 v[28:29], v215
	ds_read_b64 v[42:43], v138
	ds_read_b64 v[34:35], v216
	ds_read_b64 v[30:31], v217
	ds_read_b64 v[72:73], v218
	ds_read2_b64 v[22:25], v141 offset1:32
	ds_read_b64 v[74:75], v140
	ds_read_b64 v[38:39], v142
	ds_read_b64 v[76:77], v219
	ds_read_b64 v[78:79], v137
	s_waitcnt lgkmcnt(12)
	ds_read_b64 v[36:37], v220
	s_waitcnt lgkmcnt(7)
	v_pk_add_f16 v30, v30, v28 neg_lo:[0,1] neg_hi:[0,1]
	v_pk_add_f16 v31, v31, v29 neg_lo:[0,1] neg_hi:[0,1]
	s_waitcnt lgkmcnt(3)
	v_pk_fma_f16 v70, v30, v38, v28
	v_pk_fma_f16 v71, v31, v39, v29
	ds_read_b64 v[80:81], v139
	ds_read2_b64 v[38:41], v141 offset0:96 offset1:112
	s_waitcnt lgkmcnt(4)
	v_pk_add_f16 v82, v72, v76 neg_lo:[0,1] neg_hi:[0,1]
	v_pk_add_f16 v83, v73, v77 neg_lo:[0,1] neg_hi:[0,1]
	v_pk_add_f16 v84, v74, v42 neg_lo:[0,1] neg_hi:[0,1]
	s_waitcnt lgkmcnt(1)
	v_sub_f16_e32 v28, v80, v78
	s_waitcnt lgkmcnt(0)
	v_fma_f16 v28, v28, v38, v78
	v_fma_mix_f32 v28, v28, s86, 0 op_sel_hi:[1,0,0]
	v_lshrrev_b32_e32 v29, 16, v38
	v_exp_f32_e32 v72, v28
	v_lshrrev_b32_e32 v28, 16, v78
	v_sub_f16_sdwa v30, v80, v28 dst_sel:DWORD dst_unused:UNUSED_PAD src0_sel:WORD_1 src1_sel:DWORD
	s_nop 0
	v_fma_f16 v28, v30, v29, v28
	v_fma_mix_f32 v28, v28, s86, 0 op_sel_hi:[1,0,0]
	v_add_f32_e32 v38, 1.0, v72
	v_exp_f32_e32 v73, v28
	v_lshrrev_b32_e32 v74, 16, v79
	v_pk_add_f16 v85, v75, v43 neg_lo:[0,1] neg_hi:[0,1]
	v_sub_f16_sdwa v75, v81, v74 dst_sel:DWORD dst_unused:UNUSED_PAD src0_sel:WORD_1 src1_sel:DWORD
	v_add_f32_e32 v72, 1.0, v73
	v_sub_f16_e32 v73, v81, v79
	v_fma_f16 v73, v73, v39, v79
	v_lshrrev_b32_e32 v39, 16, v39
	v_fma_mix_f32 v73, v73, s86, 0 op_sel_hi:[1,0,0]
	v_fma_f16 v39, v75, v39, v74
	v_exp_f32_e32 v73, v73
	v_fma_mix_f32 v39, v39, s86, 0 op_sel_hi:[1,0,0]
	ds_read2_b64 v[28:31], v141 offset0:64 offset1:80
	v_exp_f32_e32 v75, v39
	v_rcp_f32_e32 v39, v72
	v_add_f32_e32 v72, 1.0, v73
	v_rcp_f32_e32 v74, v72
	v_add_f32_e32 v72, 1.0, v75
	v_rcp_f32_e32 v38, v38
	v_rcp_f32_e32 v75, v72
	v_mov_b32_e32 v11, v10
	s_waitcnt lgkmcnt(0)
	v_pk_mul_f16 v73, v71, v29
	v_pk_mul_f16 v72, v70, v28
	v_pk_fma_f32 v[28:29], v[38:39], -2.0, 1.0 op_sel_hi:[1,0,0]
	v_pk_fma_f32 v[38:39], v[74:75], -2.0, 1.0 op_sel_hi:[1,0,0]
	v_pk_fma_f16 v75, v83, v25, v77
	v_dot2c_f32_f16_e32 v11, v68, v68
	v_pk_fma_f16 v74, v82, v24, v76
	v_pk_fma_f16 v40, v84, v40, v42
	v_dot2c_f32_f16_e32 v11, v69, v69
	v_dot2c_f32_f16_e32 v11, v72, v72
	v_dot2c_f32_f16_e32 v11, v73, v73
	v_pk_fma_f16 v41, v85, v41, v43
	s_nop 1
	ds_bpermute_b32 v43, v221, v11
	v_cvt_pk_f16_f32 v25, v38, v39
	v_cvt_pk_f16_f32 v24, v28, v29
	ds_write_b64 v113, v[24:25] offset:56320
	s_waitcnt lgkmcnt(1)
	v_add_f32_e32 v11, v11, v43
	ds_bpermute_b32 v24, v222, v11
	ds_write_b64 v223, v[40:41]
	ds_write_b64 v224, v[74:75] offset:9216
	s_waitcnt lgkmcnt(2)
	s_and_saveexec_b64 s[22:23], s[0:1]
	s_cbranch_execz .LBB0_541
	s_waitcnt lgkmcnt(0)
	v_add_f32_e32 v11, v11, v24
	v_add_u32_e32 v24, s80, v97
	ds_write_b32 v24, v11

.LBB0_542:
	v_cmp_gt_i32_e64 s[22:23], s24, v89
	s_and_saveexec_b64 s[24:25], s[22:23]
	s_cbranch_execz .LBB0_544
	ds_read_b128 v[20:23], v143
	ds_read_b128 v[24:27], v145
	ds_read_b128 v[28:31], v225
	s_waitcnt lgkmcnt(1)
	v_sub_f16_e32 v8, v24, v20
	v_sub_f16_sdwa v9, v24, v20 dst_sel:DWORD dst_unused:UNUSED_PAD src0_sel:WORD_1 src1_sel:WORD_1
	v_sub_f16_e32 v11, v25, v21
	v_sub_f16_sdwa v24, v25, v21 dst_sel:DWORD dst_unused:UNUSED_PAD src0_sel:WORD_1 src1_sel:WORD_1
	v_sub_f16_e32 v32, v27, v23
	v_sub_f16_sdwa v27, v27, v23 dst_sel:DWORD dst_unused:UNUSED_PAD src0_sel:WORD_1 src1_sel:WORD_1
	v_sub_f16_e32 v25, v26, v22
	v_sub_f16_sdwa v26, v26, v22 dst_sel:DWORD dst_unused:UNUSED_PAD src0_sel:WORD_1 src1_sel:WORD_1
	v_pack_b32_f16 v27, v32, v27
	v_pack_b32_f16 v11, v11, v24
	s_waitcnt lgkmcnt(0)
	v_pk_fma_f16 v31, v31, v27, v23
	v_pack_b32_f16 v23, v25, v26
	v_pk_fma_f16 v11, v29, v11, v21
	v_pk_fma_f16 v27, v30, v23, v22
	v_fma_mix_f32 v23, v11, s87, 0 op_sel_hi:[1,0,0]
	v_cvt_f32_f16_e32 v22, v11
	v_exp_f32_e32 v24, v23
	v_fma_mix_f32 v23, v11, s87, 0 op_sel:[1,0,0] op_sel_hi:[1,0,0]
	v_pack_b32_f16 v8, v8, v9
	v_exp_f32_e32 v25, v23
	v_cvt_f32_f16_sdwa v23, v11 dst_sel:DWORD dst_unused:UNUSED_PAD src0_sel:WORD_1
	v_add_f32_e32 v11, 1.0, v24
	v_rcp_f32_e32 v24, v11
	v_add_f32_e32 v11, 1.0, v25
	v_rcp_f32_e32 v25, v11
	v_fma_mix_f32 v11, v27, s87, 0 op_sel_hi:[1,0,0]
	v_pk_fma_f16 v9, v28, v8, v20
	v_exp_f32_e32 v11, v11
	v_fma_mix_f32 v28, v27, s87, 0 op_sel:[1,0,0] op_sel_hi:[1,0,0]
	v_fma_mix_f32 v20, v9, s87, 0 op_sel_hi:[1,0,0]
	v_exp_f32_e32 v29, v28
	v_add_f32_e32 v11, 1.0, v11
	v_rcp_f32_e32 v28, v11
	v_fma_mix_f32 v21, v9, s87, 0 op_sel:[1,0,0] op_sel_hi:[1,0,0]
	v_add_f32_e32 v11, 1.0, v29
	v_rcp_f32_e32 v29, v11
	v_fma_mix_f32 v11, v31, s87, 0 op_sel_hi:[1,0,0]
	v_fma_mix_f32 v32, v31, s87, 0 op_sel:[1,0,0] op_sel_hi:[1,0,0]
	v_exp_f32_e32 v11, v11
	v_exp_f32_e32 v20, v20
	v_exp_f32_e32 v21, v21
	v_exp_f32_e32 v33, v32
	v_add_f32_e32 v11, 1.0, v11
	v_add_f32_e32 v20, 1.0, v20
	v_add_f32_e32 v21, 1.0, v21
	v_rcp_f32_e32 v32, v11
	v_add_f32_e32 v11, 1.0, v33
	v_cvt_f32_f16_e32 v8, v9
	v_cvt_f32_f16_sdwa v9, v9 dst_sel:DWORD dst_unused:UNUSED_PAD src0_sel:WORD_1
	v_rcp_f32_e32 v20, v20
	v_rcp_f32_e32 v21, v21
	v_cvt_f32_f16_e32 v26, v27
	v_cvt_f32_f16_sdwa v27, v27 dst_sel:DWORD dst_unused:UNUSED_PAD src0_sel:WORD_1
	v_cvt_f32_f16_e32 v30, v31
	v_cvt_f32_f16_sdwa v31, v31 dst_sel:DWORD dst_unused:UNUSED_PAD src0_sel:WORD_1
	v_rcp_f32_e32 v33, v11
	v_pk_fma_f32 v[8:9], v[8:9], v[20:21], 0 op_sel_hi:[1,1,0]
	v_pk_fma_f32 v[20:21], v[22:23], v[24:25], 0 op_sel_hi:[1,1,0]
	v_pk_fma_f32 v[24:25], v[26:27], v[28:29], 0 op_sel_hi:[1,1,0]
	v_pk_fma_f32 v[22:23], v[30:31], v[32:33], 0 op_sel_hi:[1,1,0]
	v_cvt_pk_f16_f32 v21, v20, v21
	v_cvt_pk_f16_f32 v23, v22, v23
	v_cvt_pk_f16_f32 v22, v24, v25
	v_cvt_pk_f16_f32 v20, v8, v9
	ds_write_b128 v146, v[20:23]

.LBB0_565:
	v_cndmask_b32_e64 v8, 0, 1, s[34:35]
	v_cmp_ne_u32_e64 s[24:25], 1, v8
	s_andn2_b64 vcc, exec, s[34:35]
	s_cbranch_vccnz .LBB0_573
	ds_read_b128 v[20:23], v226 offset:1536
	ds_read_b128 v[24:27], v226 offset:1792
	ds_read_b128 v[28:31], v226 offset:1600
	ds_read_b128 v[32:35], v226 offset:1856
	ds_read_b64 v[36:37], v115 offset:56320
	ds_read_b64 v[38:39], v116 offset:56320
	ds_read_b64 v[40:41], v227
	ds_read_b64 v[42:43], v228
	ds_read2_b64 v[82:85], v229 offset1:4
	ds_read2_b64 v[158:161], v230 offset1:4
	s_waitcnt lgkmcnt(1)
	v_mfma_f32_16x16x32_f16 v[20:23], v[82:85], v[36:39], v[20:23]
	ds_read2_b64 v[82:85], v231 offset1:4
	s_waitcnt lgkmcnt(1)
	v_mfma_f32_16x16x32_f16 v[24:27], v[158:161], v[40:43], v[24:27]
	ds_read2_b64 v[158:161], v232 offset1:4
	s_add_i32 s38, 0, 0x14800
	s_waitcnt lgkmcnt(1)
	v_mfma_f32_16x16x32_f16 v[28:31], v[82:85], v[36:39], v[28:31]
	ds_read_b64 v[36:37], v119 offset:56320
	ds_read_b64 v[38:39], v120 offset:56320
	s_waitcnt lgkmcnt(2)
	v_mfma_f32_16x16x32_f16 v[32:35], v[158:161], v[40:43], v[32:35]
	ds_read_b64 v[40:41], v233
	ds_read_b64 v[42:43], v234
	ds_read2_b64 v[82:85], v235 offset1:4
	ds_read2_b64 v[158:161], v236 offset1:4
	s_waitcnt lgkmcnt(1)
	v_mfma_f32_16x16x32_f16 v[82:85], v[82:85], v[36:39], v[20:23]
	s_nop 2
	ds_read2_b64 v[20:23], v237 offset1:4
	ds_read2_b64 v[162:165], v238 offset1:4
	s_waitcnt lgkmcnt(2)
	v_mfma_f32_16x16x32_f16 v[158:161], v[158:161], v[40:43], v[24:27]
	ds_read2st64_b32 v[8:9], v239 offset1:1
	s_waitcnt lgkmcnt(2)
	v_mfma_f32_16x16x32_f16 v[24:27], v[20:23], v[36:39], v[28:31]
	v_exp_f32_e32 v36, v82
	s_nop 3
	v_exp_f32_e32 v37, v158
	s_waitcnt lgkmcnt(0)
	v_add_f32_e32 v8, v8, v9
	v_mfma_f32_16x16x32_f16 v[20:23], v[162:165], v[40:43], v[32:35]
	v_fmamk_f32 v36, v36, 0xbf92477c, v147
	v_rcp_f32_e32 v36, v36
	v_add_f32_e32 v37, 1.0, v37
	v_rcp_f32_e32 v86, v37
	s_nop 0
	v_add_f32_dpp v37, v36, v36 row_shr:1 row_mask:0xf bank_mask:0xf bound_ctrl:1
	v_lshlrev_b32_e32 v9, 2, v240
	v_or_b32_e32 v157, 60, v9
	v_add_f32_dpp v37, v37, v37 row_shr:2 row_mask:0xf bank_mask:0xf bound_ctrl:1
	v_add_u32_e32 v32, s38, v123
	ds_read_b128 v[28:31], v32 offset:1280
	ds_read_b128 v[32:35], v32 offset:4864
	v_add_f32_dpp v37, v37, v37 row_shr:4 row_mask:0xf bank_mask:0xf bound_ctrl:1
	v_cvt_f32_f16_sdwa v165, v74 dst_sel:DWORD dst_unused:UNUSED_PAD src0_sel:WORD_1
	v_cvt_f32_f16_e32 v164, v74
	v_add_f32_dpp v82, v37, v37 row_shr:8 row_mask:0xf bank_mask:0xf bound_ctrl:1
	v_sub_f32_e32 v162, v82, v36
	v_exp_f32_e32 v36, v83
	v_exp_f32_e32 v37, v159
	ds_bpermute_b32 v40, v9, v82 offset:28
	v_max_f32_e32 v8, 0x179abe15, v8
	v_fmamk_f32 v36, v36, 0xbf92477c, v147
	v_rcp_f32_e32 v36, v36
	v_add_f32_e32 v37, 1.0, v37
	v_rcp_f32_e32 v87, v37
	v_rsq_f32_e32 v8, v8
	v_add_f32_dpp v37, v36, v36 row_shr:1 row_mask:0xf bank_mask:0xf bound_ctrl:1
	v_cvt_f32_f16_sdwa v171, v75 dst_sel:DWORD dst_unused:UNUSED_PAD src0_sel:WORD_1
	s_waitcnt lgkmcnt(1)
	v_pk_fma_f32 v[28:29], v[86:87], v[28:29], v[32:33]
	v_add_f32_dpp v37, v37, v37 row_shr:2 row_mask:0xf bank_mask:0xf bound_ctrl:1
	s_nop 1
	v_add_f32_dpp v37, v37, v37 row_shr:4 row_mask:0xf bank_mask:0xf bound_ctrl:1
	s_nop 1
	v_add_f32_dpp v83, v37, v37 row_shr:8 row_mask:0xf bank_mask:0xf bound_ctrl:1
	v_sub_f32_e32 v163, v83, v36
	v_exp_f32_e32 v36, v84
	v_exp_f32_e32 v37, v160
	ds_bpermute_b32 v41, v9, v83 offset:28
	s_waitcnt lgkmcnt(1)
	v_sub_f32_e32 v84, v162, v40
	v_fmamk_f32 v36, v36, 0xbf92477c, v147
	v_rcp_f32_e32 v36, v36
	v_add_f32_e32 v37, 1.0, v37
	v_rcp_f32_e32 v158, v37
	v_exp_f32_e32 v160, v84
	v_add_f32_dpp v37, v36, v36 row_shr:1 row_mask:0xf bank_mask:0xf bound_ctrl:1
	s_nop 1
	v_add_f32_dpp v37, v37, v37 row_shr:2 row_mask:0xf bank_mask:0xf bound_ctrl:1
	s_nop 1
	v_add_f32_dpp v37, v37, v37 row_shr:4 row_mask:0xf bank_mask:0xf bound_ctrl:1
	s_nop 1
	v_add_f32_dpp v166, v37, v37 row_shr:8 row_mask:0xf bank_mask:0xf bound_ctrl:1
	v_sub_f32_e32 v167, v166, v36
	v_exp_f32_e32 v36, v85
	v_exp_f32_e32 v37, v161
	ds_bpermute_b32 v42, v9, v166 offset:28
	ds_bpermute_b32 v38, v157, v166
	v_fmamk_f32 v36, v36, 0xbf92477c, v147
	v_rcp_f32_e32 v36, v36
	v_add_f32_e32 v37, 1.0, v37
	v_rcp_f32_e32 v159, v37
	s_waitcnt lgkmcnt(1)
	v_sub_f32_e32 v32, v167, v42
	v_add_f32_dpp v37, v36, v36 row_shr:1 row_mask:0xf bank_mask:0xf bound_ctrl:1
	v_sub_f32_e32 v33, v166, v42
	v_exp_f32_e32 v166, v33
	v_add_f32_dpp v37, v37, v37 row_shr:2 row_mask:0xf bank_mask:0xf bound_ctrl:1
	v_pk_fma_f32 v[30:31], v[158:159], v[30:31], v[34:35]
	v_exp_f32_e32 v32, v32
	v_add_f32_dpp v37, v37, v37 row_shr:4 row_mask:0xf bank_mask:0xf bound_ctrl:1
	v_rcp_f32_e32 v168, v166
	s_nop 0
	v_add_f32_dpp v169, v37, v37 row_shr:8 row_mask:0xf bank_mask:0xf bound_ctrl:1
	v_sub_f32_e32 v170, v169, v36
	ds_bpermute_b32 v36, v157, v82
	v_sub_f32_e32 v82, v82, v40
	v_exp_f32_e32 v84, v82
	v_sub_f32_e32 v82, v163, v41
	v_exp_f32_e32 v161, v82
	v_sub_f32_e32 v82, v83, v41
	ds_bpermute_b32 v43, v9, v169 offset:28
	v_exp_f32_e32 v85, v82
	ds_bpermute_b32 v37, v157, v83
	v_rcp_f32_e32 v162, v84
	v_cvt_f32_f16_sdwa v83, v66 dst_sel:DWORD dst_unused:UNUSED_PAD src0_sel:WORD_1
	v_rcp_f32_e32 v163, v85
	v_cvt_f32_f16_e32 v82, v66
	v_pk_fma_f32 v[164:165], v[164:165], v[84:85], 0 op_sel_hi:[1,1,0]
	v_cvt_f32_f16_sdwa v85, v67 dst_sel:DWORD dst_unused:UNUSED_PAD src0_sel:WORD_1
	v_cvt_f32_f16_e32 v84, v67
	s_waitcnt lgkmcnt(1)
	v_sub_f32_e32 v167, v169, v43
	v_exp_f32_e32 v167, v167
	v_pk_fma_f32 v[82:83], v[82:83], v[28:29], 0 op_sel_hi:[1,1,0]
	v_cvt_f32_f16_sdwa v29, v68 dst_sel:DWORD dst_unused:UNUSED_PAD src0_sel:WORD_1
	v_cvt_f32_f16_e32 v28, v68
	v_sub_f32_e32 v33, v170, v43
	v_pk_fma_f32 v[84:85], v[84:85], v[30:31], 0 op_sel_hi:[1,1,0]
	v_cvt_f32_f16_sdwa v31, v69 dst_sel:DWORD dst_unused:UNUSED_PAD src0_sel:WORD_1
	v_cvt_f32_f16_e32 v30, v69
	v_exp_f32_e32 v33, v33
	ds_bpermute_b32 v39, v157, v169
	v_rcp_f32_e32 v169, v167
	v_cvt_f32_f16_e32 v170, v75
	v_pk_fma_f32 v[28:29], v[28:29], v[8:9], 0 op_sel_hi:[1,0,0]
	v_pk_fma_f32 v[30:31], v[30:31], v[8:9], 0 op_sel_hi:[1,0,0]
	v_pk_mul_f32 v[34:35], v[28:29], v[160:161]
	v_pk_mul_f32 v[32:33], v[30:31], v[32:33]
	v_pk_mul_f32 v[28:29], v[86:87], v[28:29]
	v_pk_mul_f32 v[30:31], v[158:159], v[30:31]
	v_pk_fma_f32 v[166:167], v[170:171], v[166:167], 0 op_sel_hi:[1,1,0]
	v_pk_mul_f32 v[28:29], v[28:29], v[162:163]
	v_pk_mul_f32 v[30:31], v[30:31], v[168:169]
	v_pk_mul_f32 v[86:87], v[82:83], v[162:163]
	v_pk_mul_f32 v[158:159], v[84:85], v[168:169]
	v_cvt_pk_f16_f32 v33, v32, v33
	v_cvt_pk_f16_f32 v32, v34, v35
	ds_write_b64 v214, v[32:33]
	v_cvt_pk_f16_f32 v33, v166, v167
	v_cvt_pk_f16_f32 v32, v164, v165
	v_cvt_pk_f16_f32 v31, v30, v31
	v_cvt_pk_f16_f32 v30, v28, v29
	v_cvt_pk_f16_f32 v29, v158, v159
	v_cvt_pk_f16_f32 v28, v86, v87
	ds_write_b64 v214, v[32:33] offset:2304
	ds_write_b64 v214, v[30:31] offset:4608
	ds_write_b64 v214, v[28:29] offset:6912
	s_waitcnt lgkmcnt(4)
	s_and_saveexec_b64 s[34:35], s[4:5]
	s_cbranch_execz .LBB0_568
	v_add_u32_e32 v28, s71, v123
	ds_write_b128 v28, v[40:43] offset:13568
	s_waitcnt lgkmcnt(0)
	ds_write_b128 v28, v[36:39] offset:13824
.LBB0_568:
	s_or_b64 exec, exec, s[34:35]
	v_exp_f32_e32 v24, v24
	v_exp_f32_e32 v20, v20
	v_exp_f32_e32 v21, v21
	v_or_b32_e32 v40, 28, v9
	v_fmamk_f32 v24, v24, 0xbf92477c, v147
	v_rcp_f32_e32 v24, v24
	v_add_f32_e32 v20, 1.0, v20
	v_rcp_f32_e32 v36, v20
	v_add_f32_e32 v21, 1.0, v21
	v_add_f32_dpp v20, v24, v24 row_shr:1 row_mask:0xf bank_mask:0xf bound_ctrl:1
	v_rcp_f32_e32 v37, v21
	v_add_u32_e32 v32, s38, v124
	v_add_f32_dpp v20, v20, v20 row_shr:2 row_mask:0xf bank_mask:0xf bound_ctrl:1
	ds_read_b128 v[28:31], v32 offset:1280
	ds_read_b128 v[32:35], v32 offset:4864
	v_add_f32_dpp v20, v20, v20 row_shr:4 row_mask:0xf bank_mask:0xf bound_ctrl:1
	v_cvt_f32_f16_sdwa v161, v70 dst_sel:DWORD dst_unused:UNUSED_PAD src0_sel:WORD_1
	v_cvt_f32_f16_e32 v160, v70
	v_add_f32_dpp v41, v20, v20 row_shr:8 row_mask:0xf bank_mask:0xf bound_ctrl:1
	v_exp_f32_e32 v20, v25
	v_sub_f32_e32 v42, v41, v24
	ds_bpermute_b32 v24, v40, v41
	s_waitcnt lgkmcnt(1)
	v_pk_fma_f32 v[28:29], v[36:37], v[28:29], v[32:33]
	v_fmamk_f32 v20, v20, 0xbf92477c, v147
	v_rcp_f32_e32 v20, v20
	v_pk_fma_f32 v[28:29], v[160:161], v[28:29], 0 op_sel_hi:[1,1,0]
	v_cvt_f32_f16_sdwa v159, v78 dst_sel:DWORD dst_unused:UNUSED_PAD src0_sel:WORD_1
	v_cvt_f32_f16_e32 v158, v78
	v_add_f32_dpp v21, v20, v20 row_shr:1 row_mask:0xf bank_mask:0xf bound_ctrl:1
	v_cvt_f32_f16_sdwa v167, v79 dst_sel:DWORD dst_unused:UNUSED_PAD src0_sel:WORD_1
	v_cvt_f32_f16_sdwa v33, v72 dst_sel:DWORD dst_unused:UNUSED_PAD src0_sel:WORD_1
	v_add_f32_dpp v21, v21, v21 row_shr:2 row_mask:0xf bank_mask:0xf bound_ctrl:1
	v_cvt_f32_f16_e32 v32, v72
	v_mov_b32_e32 v9, v8
	v_add_f32_dpp v21, v21, v21 row_shr:4 row_mask:0xf bank_mask:0xf bound_ctrl:1
	v_pk_fma_f32 v[32:33], v[32:33], v[8:9], 0 op_sel_hi:[1,1,0]
	s_nop 0
	v_add_f32_dpp v43, v21, v21 row_shr:8 row_mask:0xf bank_mask:0xf bound_ctrl:1
	v_sub_f32_e32 v87, v43, v20
	v_exp_f32_e32 v20, v26
	v_exp_f32_e32 v21, v22
	ds_bpermute_b32 v25, v40, v43
	v_fmamk_f32 v20, v20, 0xbf92477c, v147
	v_rcp_f32_e32 v20, v20
	v_add_f32_e32 v21, 1.0, v21
	v_rcp_f32_e32 v38, v21
	s_nop 0
	v_add_f32_dpp v21, v20, v20 row_shr:1 row_mask:0xf bank_mask:0xf bound_ctrl:1
	s_nop 1
	v_add_f32_dpp v21, v21, v21 row_shr:2 row_mask:0xf bank_mask:0xf bound_ctrl:1
	s_nop 1
	v_add_f32_dpp v21, v21, v21 row_shr:4 row_mask:0xf bank_mask:0xf bound_ctrl:1
	s_nop 1
	v_add_f32_dpp v162, v21, v21 row_shr:8 row_mask:0xf bank_mask:0xf bound_ctrl:1
	v_sub_f32_e32 v163, v162, v20
	v_exp_f32_e32 v20, v27
	v_exp_f32_e32 v21, v23
	ds_bpermute_b32 v26, v40, v162
	ds_bpermute_b32 v22, v157, v162
	v_fmamk_f32 v20, v20, 0xbf92477c, v147
	v_rcp_f32_e32 v20, v20
	v_add_f32_e32 v21, 1.0, v21
	v_rcp_f32_e32 v39, v21
	s_nop 0
	v_add_f32_dpp v21, v20, v20 row_shr:1 row_mask:0xf bank_mask:0xf bound_ctrl:1
	v_pk_fma_f32 v[30:31], v[38:39], v[30:31], v[34:35]
	s_nop 0
	v_add_f32_dpp v21, v21, v21 row_shr:2 row_mask:0xf bank_mask:0xf bound_ctrl:1
	v_cvt_f32_f16_sdwa v35, v73 dst_sel:DWORD dst_unused:UNUSED_PAD src0_sel:WORD_1
	v_cvt_f32_f16_e32 v34, v73
	v_add_f32_dpp v21, v21, v21 row_shr:4 row_mask:0xf bank_mask:0xf bound_ctrl:1
	v_pk_fma_f32 v[8:9], v[34:35], v[8:9], 0 op_sel_hi:[1,1,0]
	s_nop 0
	v_add_f32_dpp v165, v21, v21 row_shr:8 row_mask:0xf bank_mask:0xf bound_ctrl:1
	ds_bpermute_b32 v27, v40, v165
	v_sub_f32_e32 v166, v165, v20
	ds_bpermute_b32 v20, v157, v41
	ds_bpermute_b32 v21, v157, v43
	ds_bpermute_b32 v23, v157, v165
	s_waitcnt lgkmcnt(5)
	v_sub_f32_e32 v157, v163, v26
	v_exp_f32_e32 v160, v157
	v_sub_f32_e32 v157, v162, v26
	v_exp_f32_e32 v162, v157
	s_waitcnt lgkmcnt(3)
	v_sub_f32_e32 v157, v166, v27
	v_sub_f32_e32 v41, v41, v24
	v_sub_f32_e32 v43, v43, v25
	v_exp_f32_e32 v161, v157
	v_sub_f32_e32 v157, v165, v27
	v_sub_f32_e32 v40, v42, v24
	v_exp_f32_e32 v42, v41
	v_exp_f32_e32 v43, v43
	v_exp_f32_e32 v163, v157
	v_cvt_f32_f16_e32 v166, v79
	v_sub_f32_e32 v41, v87, v25
	v_exp_f32_e32 v40, v40
	v_exp_f32_e32 v41, v41
	v_rcp_f32_e32 v86, v42
	v_rcp_f32_e32 v87, v43
	v_rcp_f32_e32 v164, v162
	v_rcp_f32_e32 v165, v163
	v_pk_fma_f32 v[42:43], v[158:159], v[42:43], 0 op_sel_hi:[1,1,0]
	v_pk_fma_f32 v[158:159], v[166:167], v[162:163], 0 op_sel_hi:[1,1,0]
	v_cvt_f32_f16_sdwa v163, v71 dst_sel:DWORD dst_unused:UNUSED_PAD src0_sel:WORD_1
	v_cvt_f32_f16_e32 v162, v71
	v_pk_mul_f32 v[34:35], v[32:33], v[40:41]
	v_pk_mul_f32 v[40:41], v[8:9], v[160:161]
	v_pk_mul_f32 v[32:33], v[36:37], v[32:33]
	v_pk_mul_f32 v[8:9], v[38:39], v[8:9]
	v_pk_fma_f32 v[30:31], v[162:163], v[30:31], 0 op_sel_hi:[1,1,0]
	v_pk_mul_f32 v[32:33], v[32:33], v[86:87]
	v_pk_mul_f32 v[8:9], v[8:9], v[164:165]
	v_pk_mul_f32 v[36:37], v[28:29], v[86:87]
	v_pk_mul_f32 v[38:39], v[30:31], v[164:165]
	v_add_u32_e32 v86, s71, v114
	v_cvt_pk_f16_f32 v9, v8, v9
	v_cvt_pk_f16_f32 v8, v32, v33
	v_cvt_pk_f16_f32 v41, v40, v41
	v_cvt_pk_f16_f32 v40, v34, v35
	v_cvt_pk_f16_f32 v35, v158, v159
	v_cvt_pk_f16_f32 v34, v42, v43
	ds_write_b64 v86, v[8:9] offset:4608
	v_cvt_pk_f16_f32 v9, v38, v39
	v_cvt_pk_f16_f32 v8, v36, v37
	ds_write_b64 v86, v[40:41]
	ds_write_b64 v86, v[34:35] offset:2304
	ds_write_b64 v86, v[8:9] offset:6912
	s_waitcnt lgkmcnt(4)
	s_and_saveexec_b64 s[34:35], s[4:5]
	s_cbranch_execz .LBB0_570
	v_add_u32_e32 v8, s71, v124
	ds_write_b128 v8, v[24:27] offset:13568
	ds_write_b128 v8, v[20:23] offset:13824
.LBB0_570:
	s_or_b64 exec, exec, s[34:35]
	v_fma_mix_f32 v8, v76, v82, 0 op_sel_hi:[1,0,0]
	s_nop 0
	v_fma_mix_f32 v8, v76, v83, v8 op_sel:[1,0,0] op_sel_hi:[1,0,0]
	v_add_u32_e32 v11, 64, v241
	v_fma_mix_f32 v8, v77, v84, v8 op_sel_hi:[1,0,0]
	v_cmp_lt_i32_e32 vcc, v242, v11
	v_fma_mix_f32 v8, v77, v85, v8 op_sel:[1,0,0] op_sel_hi:[1,0,0]
	s_nop 0
	v_fma_mix_f32 v8, v80, v28, v8 op_sel_hi:[1,0,0]
	v_cndmask_b32_e32 v9, v144, v242, vcc
	v_fma_mix_f32 v8, v80, v29, v8 op_sel:[1,0,0] op_sel_hi:[1,0,0]
	v_lshlrev_b32_e32 v9, 2, v9
	v_fma_mix_f32 v8, v81, v30, v8 op_sel_hi:[1,0,0]
	s_nop 0
	v_fma_mix_f32 v8, v81, v31, v8 op_sel:[1,0,0] op_sel_hi:[1,0,0]
	s_nop 0
	ds_bpermute_b32 v9, v9, v8
	s_waitcnt lgkmcnt(0)
	v_add_f32_e32 v8, v8, v9
	v_cmp_lt_i32_e32 vcc, v243, v11
	s_nop 1
	v_cndmask_b32_e32 v9, v144, v243, vcc
	v_lshlrev_b32_e32 v9, 2, v9
	ds_bpermute_b32 v9, v9, v8
	s_waitcnt lgkmcnt(0)
	s_nop 0
	s_and_saveexec_b64 s[34:35], s[0:1]
	s_cbranch_execz .LBB0_572
	s_waitcnt lgkmcnt(0)
	v_add_f32_e32 v8, v8, v9
	v_add_u32_e32 v9, s84, v97
	ds_write_b32 v9, v8

.LBB0_578:
	s_cmp_eq_u32 s28, s29
	s_waitcnt lgkmcnt(0)
	s_barrier
	s_cselect_b64 s[24:25], -1, 0
	s_or_b64 s[24:25], s[54:55], s[24:25]
	s_and_b64 vcc, exec, s[24:25]
	s_cbranch_vccnz .LBB0_581
	s_min_u32 s24, s33, 64
	s_lshr_b32 s24, s24, 4
	s_max_u32 s24, s24, 1
	v_mov_b32_e32 v42, v125
	v_mov_b32_e32 v43, v130
	v_mov_b32_e32 v82, v129
	v_mov_b32_e32 v83, v128
	v_mov_b32_e32 v84, v105
	v_mov_b32_e32 v85, v127
	v_mov_b32_e32 v86, v126
	s_waitcnt lgkmcnt(0)
.LBB0_580:
	v_add_u32_e32 v8, 0, v42
	v_add_u32_e32 v26, 0, v84
	v_add_u32_e32 v157, 0, v43
	v_add_u32_e32 v87, 0, v82
	v_add_u32_e32 v9, 0, v83
	v_add_u32_e32 v22, 0, v85
	ds_read2_b64 v[178:181], v8 offset1:4
	ds_read_b128 v[182:185], v87
	ds_read_b128 v[186:189], v87 offset:64
	ds_read2_b64 v[190:193], v8 offset0:8 offset1:12
	ds_read_b64_tr_b16 v[30:31], v9
	ds_read2st64_b64 v[194:197], v22 offset1:1
	ds_read_b128 v[198:201], v157
	ds_read_b128 v[202:205], v87 offset:128
	ds_read_b64_tr_b16 v[158:159], v26 offset:6912
	ds_read_b64_tr_b16 v[162:163], v26 offset:6944
	ds_read_b64_tr_b16 v[166:167], v26 offset:6976
	s_waitcnt lgkmcnt(12)
	ds_read_b64_tr_b16 v[170:171], v26 offset:7008
	s_waitcnt lgkmcnt(12)
	ds_read_b64_tr_b16 v[38:39], v26 offset:4608
	s_waitcnt lgkmcnt(5)
	v_pk_mul_f32 v[16:17], v[16:17], v[202:203]
	v_add_u32_e32 v202, 0x800, v8
	v_pk_mul_f32 v[18:19], v[18:19], v[204:205]
	v_pk_mul_f32 v[14:15], v[14:15], v[188:189]
	v_cvt_pk_f16_f32 v189, v18, v19
	v_cvt_pk_f16_f32 v188, v16, v17
	v_pk_mul_f32 v[6:7], v[6:7], v[184:185]
	v_pk_mul_f32 v[4:5], v[4:5], v[182:183]
	ds_read2st64_b64 v[182:185], v22 offset0:2 offset1:3
	s_waitcnt lgkmcnt(2)
	v_mfma_f32_16x16x16_f16 v[170:173], v[170:171], v[30:31], v[16:19]
	v_pk_mul_f32 v[12:13], v[12:13], v[186:187]
	v_mfma_f32_16x16x16_f16 v[16:19], v[194:195], v[30:31], 0
	v_mul_f32_e64 v2, v2, v200
	v_mul_f32_e64 v3, v3, v201
	v_pk_mul_f32 v[0:1], v[0:1], v[198:199]
	v_cvt_pk_f16_f32 v187, v14, v15
	v_cvt_pk_f16_f32 v186, v12, v13
	v_cvt_pk_f16_f32 v201, v6, v7
	v_cvt_pk_f16_f32 v199, v2, v3
	v_cvt_pk_f16_f32 v200, v4, v5
	v_cvt_pk_f16_f32 v198, v0, v1
	v_mfma_f32_16x16x32_f16 v[190:193], v[190:193], v[186:189], 0
	v_mfma_f32_16x16x16_f16 v[162:165], v[162:163], v[30:31], v[4:7]
	v_mfma_f32_16x16x32_f16 v[4:7], v[178:181], v[198:201], v[16:19]
	v_mfma_f32_16x16x16_f16 v[12:15], v[166:167], v[30:31], v[12:15]
	ds_read_b64_tr_b16 v[174:175], v26 offset:4640
	ds_read2_b64 v[166:169], v202 offset0:40 offset1:44
	ds_read_b64_tr_b16 v[22:23], v26 offset:4672
	s_nop 3
	v_pk_add_f32 v[6:7], v[6:7], v[192:193]
	v_pk_add_f32 v[4:5], v[4:5], v[190:191]
	v_cvt_pk_f16_f32 v35, v6, v7
	v_cvt_pk_f16_f32 v34, v4, v5
	s_waitcnt lgkmcnt(3)
	s_nop 0
	v_mfma_f32_16x16x16_f16 v[4:7], v[184:185], v[34:35], 0
	v_mfma_f32_16x16x16_f16 v[158:161], v[158:159], v[30:31], v[0:3]
	s_nop 6
	v_xor_b32_e32 v16, 0x80000000, v7
	v_xor_b32_e32 v17, 0x80000000, v6
	v_xor_b32_e32 v5, 0x80000000, v5
	s_waitcnt lgkmcnt(1)
	v_mfma_f32_16x16x32_f16 v[0:3], v[166:169], v[186:189], 0
	v_xor_b32_e32 v4, 0x80000000, v4
	v_cvt_pk_f16_f32 v19, v17, v16
	v_cvt_pk_f16_f32 v18, v4, v5
	v_mfma_f32_16x16x16_f16 v[6:9], v[196:197], v[30:31], 0
	s_add_i32 s24, s24, -1
	v_mfma_f32_16x16x16_f16 v[30:33], v[38:39], v[18:19], v[158:161]
	ds_read_b64_tr_b16 v[26:27], v26 offset:4704
	ds_read_b128 v[38:41], v157 offset:256
	s_nop 0
	ds_read_b128 v[158:161], v87 offset:256
	v_add_u32_e32 v206, 0, v86
	v_add_u32_e32 v86, 0x1000, v86
	v_mfma_f32_16x16x16_f16 v[34:37], v[174:175], v[18:19], v[162:165]
	v_add_u32_e32 v85, 0x3700, v85
	v_add_u32_e32 v84, 0x3700, v84
	v_add_u32_e32 v83, 0x3700, v83
	s_waitcnt lgkmcnt(3)
	v_mfma_f32_16x16x16_f16 v[12:15], v[22:23], v[18:19], v[12:15]
	ds_read_b128 v[22:25], v87 offset:320
	ds_read_b128 v[162:165], v87 offset:384
	v_add_u32_e32 v82, 0x3700, v82
	v_add_u32_e32 v43, 0x3700, v43
	v_mfma_f32_16x16x16_f16 v[166:169], v[182:183], v[18:19], v[0:3]
	v_add_u32_e32 v42, 0x3700, v42
	s_waitcnt lgkmcnt(2)
	v_pk_mul_f32 v[4:5], v[158:159], v[34:35]
	ds_read2_b64 v[0:3], v202 offset0:32 offset1:36
	v_mfma_f32_16x16x16_f16 v[26:29], v[26:27], v[18:19], v[170:173]
	s_waitcnt lgkmcnt(2)
	v_pk_mul_f32 v[14:15], v[24:25], v[14:15]
	v_pk_mul_f32 v[12:13], v[22:23], v[12:13]
	s_waitcnt lgkmcnt(0)
	v_mfma_f32_16x16x32_f16 v[170:173], v[0:3], v[198:201], v[6:9]
	v_mul_f32_e64 v2, v40, v32
	v_mul_f32_e64 v3, v41, v33
	v_pk_mul_f32 v[0:1], v[38:39], v[30:31]
	v_pk_mul_f32 v[6:7], v[160:161], v[36:37]
	v_pk_mul_f32 v[18:19], v[164:165], v[28:29]
	v_pk_mul_f32 v[16:17], v[162:163], v[26:27]
	s_nop 1
	v_pk_add_f32 v[20:21], v[170:171], v[166:167]
	v_pk_add_f32 v[8:9], v[172:173], v[168:169]
	ds_write2st64_b32 v206, v20, v21 offset1:1
	ds_write2st64_b32 v206, v8, v9 offset0:2 offset1:3
	s_cmp_lg_u32 s24, 0
	s_cbranch_scc1 .LBB0_580

.LBB0_718:
	s_or_b64 exec, exec, s[0:1]
	s_cmpk_lt_i32 s2, 0x84
	s_mov_b32 s29, s74
	s_cselect_b64 s[74:75], -1, 0
	s_add_u32 s33, s76, 0x1180000
	s_addc_u32 s49, s77, 0
	s_add_u32 s36, s76, 0xfe000000
	s_addc_u32 s37, s77, -1
	s_add_u32 s38, s76, 0xfe080000
	s_addc_u32 s39, s77, -1
	s_add_u32 s42, s76, 0x2800000
	s_addc_u32 s43, s77, 0
	v_cndmask_b32_e64 v0, 0, 1, s[4:5]
	s_cmpk_gt_i32 s2, 0x83
	v_cmp_ne_u32_e64 s[0:1], 1, v0
	s_barrier
	s_cbranch_scc1 .LBB0_1022
	v_mbcnt_lo_u32_b32 v0, -1, 0
	v_mbcnt_hi_u32_b32 v0, -1, v0
	v_lshlrev_b32_e32 v0, 2, v0
	v_lshl_add_u32 v0, s97, 3, v0
	v_add_u32_e32 v0, 0x24000, v0
	v_writelane_b32 v1, s0, 0
	v_writelane_b32 v1, s1, 1
	v_writelane_b32 v1, s2, 2
	v_writelane_b32 v1, s3, 3
	v_writelane_b32 v1, s4, 4
	v_writelane_b32 v1, s5, 5
	v_writelane_b32 v1, s6, 6
	v_writelane_b32 v1, s7, 7
	v_writelane_b32 v1, s8, 8
	v_writelane_b32 v1, s9, 9
	v_writelane_b32 v1, s10, 10
	v_writelane_b32 v1, s11, 11
	v_writelane_b32 v1, s12, 12
	v_writelane_b32 v1, s13, 13
	v_writelane_b32 v1, s14, 14
	v_writelane_b32 v1, s15, 15
	v_writelane_b32 v1, s16, 16
	v_writelane_b32 v1, s17, 17
	v_writelane_b32 v1, s18, 18
	v_writelane_b32 v1, s19, 19
	v_writelane_b32 v1, s20, 20
	v_writelane_b32 v1, s21, 21
	v_writelane_b32 v1, s22, 22
	v_writelane_b32 v1, s23, 23
	v_writelane_b32 v1, s24, 24
	v_writelane_b32 v1, s25, 25
	v_writelane_b32 v1, s26, 26
	v_writelane_b32 v1, s27, 27
	v_writelane_b32 v1, s28, 28
	v_writelane_b32 v1, s29, 29
	v_writelane_b32 v1, s30, 30
	v_writelane_b32 v1, s31, 31
	v_writelane_b32 v1, s32, 32
	v_writelane_b32 v1, s33, 33
	v_writelane_b32 v1, s34, 34
	v_writelane_b32 v1, s35, 35
	v_writelane_b32 v1, s36, 36
	v_writelane_b32 v1, s37, 37
	v_writelane_b32 v1, s38, 38
	v_writelane_b32 v1, s39, 39
	v_writelane_b32 v1, s40, 40
	v_writelane_b32 v1, s41, 41
	v_writelane_b32 v1, s42, 42
	v_writelane_b32 v1, s43, 43
	v_writelane_b32 v1, s44, 44
	v_writelane_b32 v1, s45, 45
	v_writelane_b32 v1, s46, 46
	v_writelane_b32 v1, s47, 47
	v_writelane_b32 v1, s48, 48
	v_writelane_b32 v1, s49, 49
	v_writelane_b32 v1, s50, 50
	v_writelane_b32 v1, s51, 51
	v_writelane_b32 v1, s52, 52
	v_writelane_b32 v1, s53, 53
	v_writelane_b32 v1, s54, 54
	v_writelane_b32 v1, s55, 55
	v_writelane_b32 v1, s56, 56
	v_writelane_b32 v1, s57, 57
	v_writelane_b32 v1, s58, 58
	v_writelane_b32 v1, s59, 59
	v_writelane_b32 v1, s60, 60
	v_writelane_b32 v1, s61, 61
	v_writelane_b32 v1, s62, 62
	v_writelane_b32 v1, s63, 63
	ds_write_b32 v0, v1
	s_nop 1
	v_writelane_b32 v1, s64, 0
	v_writelane_b32 v1, s65, 1
	v_writelane_b32 v1, s66, 2
	v_writelane_b32 v1, s67, 3
	v_writelane_b32 v1, s68, 4
	v_writelane_b32 v1, s69, 5
	v_writelane_b32 v1, s70, 6
	v_writelane_b32 v1, s71, 7
	v_writelane_b32 v1, s72, 8
	v_writelane_b32 v1, s73, 9
	v_writelane_b32 v1, s74, 10
	v_writelane_b32 v1, s75, 11
	v_writelane_b32 v1, s76, 12
	v_writelane_b32 v1, s77, 13
	v_writelane_b32 v1, s78, 14
	v_writelane_b32 v1, s79, 15
	v_writelane_b32 v1, s80, 16
	v_writelane_b32 v1, s81, 17
	v_writelane_b32 v1, s82, 18
	v_writelane_b32 v1, s83, 19
	v_writelane_b32 v1, s84, 20
	v_writelane_b32 v1, s85, 21
	v_writelane_b32 v1, s86, 22
	v_writelane_b32 v1, s87, 23
	v_writelane_b32 v1, s88, 24
	v_writelane_b32 v1, s89, 25
	v_writelane_b32 v1, s90, 26
	v_writelane_b32 v1, s91, 27
	v_writelane_b32 v1, s92, 28
	v_writelane_b32 v1, s93, 29
	v_writelane_b32 v1, s94, 30
	v_writelane_b32 v1, s95, 31
	v_writelane_b32 v1, s96, 32
	v_writelane_b32 v1, s97, 33
	ds_write_b32 v0, v1 offset:256
	s_waitcnt lgkmcnt(0)
	s_branch .LBB0_1022
.Ltail_entry:
	v_mbcnt_lo_u32_b32 v3, -1, 0
	v_mbcnt_hi_u32_b32 v3, -1, v3
	s_mov_b32 s3, 0x1fffe0
	v_lshl_or_b32 v4, v3, 4, s66
	v_ashrrev_i32_e32 v0, 31, v4
	v_lshrrev_b32_e32 v0, 22, v0
	v_add_u32_e32 v0, v4, v0
	v_ashrrev_i32_e32 v0, 10, v0
	v_mul_i32_i24_e32 v1, 0x400, v0
	v_sub_u32_e32 v1, v4, v1
	v_lshrrev_b32_e32 v2, 4, v1
	v_bitop3_b32 v2, v2, v1, 32 bitop3:0x6c
	v_lshlrev_b32_e32 v1, 3, v0
	v_and_b32_e32 v5, -16, v1
	v_ashrrev_i32_e32 v1, 31, v2
	v_lshrrev_b32_e32 v1, 26, v1
	v_add_u32_e32 v6, v2, v1
	v_ashrrev_i32_e32 v1, 6, v6
	v_and_b32_e32 v6, 0xc0, v6
	v_sub_u32_e32 v2, v2, v6
	v_mov_b32_e32 v6, 1
	v_lshlrev_b32_e32 v7, 5, v0
	v_ashrrev_i16_sdwa v2, v6, sext(v2) dst_sel:DWORD dst_unused:UNUSED_PAD src0_sel:DWORD src1_sel:BYTE_0
	v_and_b32_e32 v7, 32, v7
	v_bfe_i32 v2, v2, 0, 16
	v_add_u32_e32 v5, v1, v5
	v_and_b32_e32 v10, 3, v1
	v_add_lshl_u32 v7, v7, v2, 1
	v_lshlrev_b32_e32 v8, 1, v5
	v_lshrrev_b32_e32 v9, 2, v5
	v_and_or_b32 v10, v5, s3, v10
	v_lshl_add_u32 v128, v5, 11, v7
	v_add_u32_e32 v5, 0x2000, v4
	v_ashrrev_i32_e32 v4, 31, v5
	v_lshrrev_b32_e32 v4, 22, v4
	v_and_b32_e32 v8, 24, v8
	v_and_b32_e32 v9, 4, v9
	v_add_u32_e32 v4, v5, v4
	v_or3_b32 v8, v10, v9, v8
	v_ashrrev_i32_e32 v4, 10, v4
	s_add_u32 s4, s76, 0x6800000
	v_lshl_add_u32 v130, v8, 11, v7
	v_mul_i32_i24_e32 v7, 0x400, v4
	s_addc_u32 s5, s77, 0
	s_ashr_i32 s31, s30, 31
	v_sub_u32_e32 v5, v5, v7
	s_lshl_b64 s[10:11], s[30:31], 19
	v_lshrrev_b32_e32 v7, 4, v5
	s_add_u32 s18, s33, s10
	v_bitop3_b32 v7, v7, v5, 32 bitop3:0x6c
	v_lshlrev_b32_e32 v5, 3, v4
	s_addc_u32 s19, s49, s11
	v_and_b32_e32 v8, -16, v5
	v_ashrrev_i32_e32 v5, 31, v7
	s_add_u32 s14, s18, 0x40000
	v_lshrrev_b32_e32 v5, 26, v5
	s_addc_u32 s15, s19, 0
	v_add_u32_e32 v9, v7, v5
	s_add_u32 s6, s76, 0x6840000
	v_ashrrev_i32_e32 v5, 6, v9
	v_and_b32_e32 v9, 0xffc0, v9
	s_addc_u32 s7, s77, 0
	v_sub_u32_e32 v7, v7, v9
	s_add_u32 s12, s76, 0x6800080
	v_lshrrev_b16_e32 v9, 7, v7
	s_addc_u32 s13, s77, 0
	v_and_b32_e32 v9, 1, v9
	s_add_u32 s8, s18, 0x40080
	v_add_u32_e32 v8, v5, v8
	v_add_u16_e32 v7, v7, v9
	s_addc_u32 s9, s19, 0
	v_lshlrev_b32_e32 v10, 5, v4
	v_ashrrev_i16_sdwa v6, v6, sext(v7) dst_sel:DWORD dst_unused:UNUSED_PAD src0_sel:DWORD src1_sel:BYTE_0
	v_lshlrev_b32_e32 v7, 1, v8
	v_lshrrev_b32_e32 v9, 2, v8
	v_and_b32_e32 v11, 3, v5
	s_add_i32 s61, s66, 0
	v_and_b32_e32 v10, 32, v10
	v_bfe_i32 v6, v6, 0, 16
	v_and_b32_e32 v7, 24, v7
	v_and_b32_e32 v9, 4, v9
	v_and_or_b32 v11, v8, s3, v11
	s_add_i32 s44, s61, 0x10000
	v_or3_b32 v7, v11, v9, v7
	v_add_lshl_u32 v9, v10, v6, 1
	s_mov_b32 m0, s44
	s_add_i32 s93, s61, 0x12000
	v_lshl_add_u32 v134, v7, 11, v9
	global_load_lds_dwordx4 v130, s[18:19]
	s_mov_b32 m0, s93
	s_add_i32 s94, s61, 0x14000
	global_load_lds_dwordx4 v134, s[18:19]
	s_mov_b32 m0, s94
	s_add_i32 s95, s61, 0x16000
	global_load_lds_dwordx4 v130, s[14:15]
	s_mov_b32 m0, s95
	s_add_i32 s71, s61, 0x2000
	global_load_lds_dwordx4 v134, s[14:15]
	s_mov_b32 m0, s61
	v_lshl_add_u32 v132, v8, 11, v9
	global_load_lds_dwordx4 v128, s[4:5]
	s_mov_b32 m0, s71
	s_add_i32 s47, s61, 0x4000
	v_mov_b32_e32 v137, 0
	global_load_lds_dwordx4 v132, s[4:5]
	s_mov_b32 m0, s47
	s_add_i32 s58, s61, 0x6000
	v_mov_b32_e32 v131, v137
	global_load_lds_dwordx4 v128, s[6:7]
	s_mov_b32 m0, s58
	v_lshl_add_u64 v[8:9], s[18:19], 0, v[130:131]
	v_mov_b32_e32 v135, v137
	global_load_lds_dwordx4 v132, s[6:7]
	s_mov_b64 s[6:7], 0x80
	s_add_i32 s89, s61, 0x18000
	v_lshl_add_u64 v[10:11], s[18:19], 0, v[134:135]
	v_lshl_add_u64 v[8:9], v[8:9], 0, s[6:7]
	s_mov_b32 m0, s89
	s_add_i32 s90, s61, 0x1a000
	global_load_lds_dwordx4 v[8:9], off
	v_lshl_add_u64 v[8:9], v[10:11], 0, s[6:7]
	s_mov_b32 m0, s90
	s_add_i32 s34, s61, 0x8000
	global_load_lds_dwordx4 v[8:9], off
	s_mov_b32 m0, s34
	s_add_i32 s35, s61, 0xa000
	global_load_lds_dwordx4 v128, s[12:13]
	s_mov_b32 m0, s35
	s_add_i32 s91, s61, 0x1c000
	global_load_lds_dwordx4 v132, s[12:13]
	s_mov_b32 m0, s91
	s_add_i32 s92, s61, 0x1e000
	global_load_lds_dwordx4 v130, s[8:9]
	s_mov_b32 m0, s92
	s_and_b64 vcc, exec, s[0:1]
	global_load_lds_dwordx4 v134, s[8:9]
	s_mov_b32 s9, 0
	s_cbranch_vccnz .LBB0_721
	s_barrier

.LBB0_1021:
	s_or_b64 exec, exec, s[4:5]
	s_waitcnt lgkmcnt(0)
	s_barrier
	s_waitcnt vmcnt(0)
	s_barrier
	s_branch .Lmq_setup

.LBB0_1027:
	v_and_b32_e32 v7, 15, v0
	v_and_b32_e32 v8, 48, v0
	v_lshlrev_b32_e32 v0, 2, v0
	v_lshl_or_b32 v9, v7, 6, v8
	v_and_b32_e32 v0, 32, v0
	s_and_b64 s[8:9], s[74:75], exec
	v_bitop3_b32 v10, v9, s52, v0 bitop3:0xde
	v_bitop3_b32 v144, v9, s53, v0 bitop3:0xde
	s_movk_i32 s58, 12
	v_or_b32_e32 v0, s54, v8
	v_lshl_or_b32 v7, v7, 11, s55
	s_add_i32 s59, s58, 2
	v_or_b32_e32 v145, v7, v0
	v_add_u32_e32 v0, v7, v0
	s_cmpk_gt_i32 s2, 0x83
	v_add_u32_e32 v149, 0x40000, v0
	v_add_u32_e32 v150, 0x48000, v0
	v_add_u32_e32 v151, 0x50000, v0
	v_add_u32_e32 v152, 0x58000, v0
	v_lshlrev_b32_e32 v0, 14, v1
	s_mov_b64 s[8:9], 0
	s_cmp_lt_u32 s30, 12
	v_and_b32_e32 v0, 0xffff8000, v0
	s_cselect_b64 s[10:11], -1, 0
	s_lshl_b32 s12, s30, 5
	v_lshl_add_u32 v0, v2, 11, v0
	v_and_b32_e32 v1, 1, v1
	s_and_b32 s5, s2, 3
	s_and_b32 s13, s12, 0x380
	s_and_b32 s12, s12, 0x180
	v_lshl_or_b32 v0, v1, 6, v0
	s_or_b32 s61, s13, s5
	s_or_b32 s62, s12, s5
	v_lshl_add_u32 v138, v3, 1, v0
	v_lshlrev_b32_e32 v0, 14, v4
	s_addk_i32 s61, 0xff80
	s_addk_i32 s62, 0x80
	s_add_i32 s5, s2, 0xffffff74
	v_and_b32_e32 v0, 0xffff8000, v0
	s_waitcnt vmcnt(8)
	s_barrier
	s_waitcnt vmcnt(6)
	s_cmp_lt_u32 s5, 8
	v_lshl_add_u32 v0, v5, 11, v0
	v_and_b32_e32 v1, 1, v4
	s_mov_b64 s[12:13], 0
	v_lshl_or_b32 v0, v1, 6, v0
	s_add_i32 s70, 0, 0x14000
	s_add_i32 s71, 0, 0x1c000
	v_or_b32_e32 v146, 0x8000, v145
	v_or_b32_e32 v147, 0x10000, v145
	v_or_b32_e32 v148, 0x18000, v145
	v_mov_b32_e32 v139, v137
	v_lshl_add_u32 v140, v6, 1, v0
	v_mov_b32_e32 v141, v137
	s_mov_b32 s68, 0x1380000
	s_mov_b32 s69, 0x2800000
	s_mov_b64 s[14:15], 0x100
	v_add_u32_e32 v153, s70, v144
	v_add_u32_e32 v154, 0, v10
	v_add_u32_e32 v155, s71, v144
	s_mov_b32 s80, 0
	s_barrier
	s_branch .LBB0_1030

.LBB0_1198:
	s_or_b64 exec, exec, s[4:5]
	s_cmpk_gt_i32 s2, 0x83
	s_cbranch_scc1 .Lmq_setup
	v_mbcnt_lo_u32_b32 v0, -1, 0
	v_mbcnt_hi_u32_b32 v0, -1, v0
	v_lshlrev_b32_e32 v0, 2, v0
	v_lshl_add_u32 v0, s97, 3, v0
	v_add_u32_e32 v0, 0x24000, v0
	ds_read_b32 v1, v0
	ds_read_b32 v2, v0 offset:256
	s_waitcnt lgkmcnt(0)
	v_readlane_b32 s0, v1, 0
	v_readlane_b32 s1, v1, 1
	v_readlane_b32 s2, v1, 2
	v_readlane_b32 s3, v1, 3
	v_readlane_b32 s4, v1, 4
	v_readlane_b32 s5, v1, 5
	v_readlane_b32 s6, v1, 6
	v_readlane_b32 s7, v1, 7
	v_readlane_b32 s8, v1, 8
	v_readlane_b32 s9, v1, 9
	v_readlane_b32 s10, v1, 10
	v_readlane_b32 s11, v1, 11
	v_readlane_b32 s12, v1, 12
	v_readlane_b32 s13, v1, 13
	v_readlane_b32 s14, v1, 14
	v_readlane_b32 s15, v1, 15
	v_readlane_b32 s16, v1, 16
	v_readlane_b32 s17, v1, 17
	v_readlane_b32 s18, v1, 18
	v_readlane_b32 s19, v1, 19
	v_readlane_b32 s20, v1, 20
	v_readlane_b32 s21, v1, 21
	v_readlane_b32 s22, v1, 22
	v_readlane_b32 s23, v1, 23
	v_readlane_b32 s24, v1, 24
	v_readlane_b32 s25, v1, 25
	v_readlane_b32 s26, v1, 26
	v_readlane_b32 s27, v1, 27
	v_readlane_b32 s28, v1, 28
	v_readlane_b32 s29, v1, 29
	v_readlane_b32 s30, v1, 30
	v_readlane_b32 s31, v1, 31
	v_readlane_b32 s32, v1, 32
	v_readlane_b32 s33, v1, 33
	v_readlane_b32 s34, v1, 34
	v_readlane_b32 s35, v1, 35
	v_readlane_b32 s36, v1, 36
	v_readlane_b32 s37, v1, 37
	v_readlane_b32 s38, v1, 38
	v_readlane_b32 s39, v1, 39
	v_readlane_b32 s40, v1, 40
	v_readlane_b32 s41, v1, 41
	v_readlane_b32 s42, v1, 42
	v_readlane_b32 s43, v1, 43
	v_readlane_b32 s44, v1, 44
	v_readlane_b32 s45, v1, 45
	v_readlane_b32 s46, v1, 46
	v_readlane_b32 s47, v1, 47
	v_readlane_b32 s48, v1, 48
	v_readlane_b32 s49, v1, 49
	v_readlane_b32 s50, v1, 50
	v_readlane_b32 s51, v1, 51
	v_readlane_b32 s52, v1, 52
	v_readlane_b32 s53, v1, 53
	v_readlane_b32 s54, v1, 54
	v_readlane_b32 s55, v1, 55
	v_readlane_b32 s56, v1, 56
	v_readlane_b32 s57, v1, 57
	v_readlane_b32 s58, v1, 58
	v_readlane_b32 s59, v1, 59
	v_readlane_b32 s60, v1, 60
	v_readlane_b32 s61, v1, 61
	v_readlane_b32 s62, v1, 62
	v_readlane_b32 s63, v1, 63
	v_readlane_b32 s64, v2, 0
	v_readlane_b32 s65, v2, 1
	v_readlane_b32 s66, v2, 2
	v_readlane_b32 s67, v2, 3
	v_readlane_b32 s68, v2, 4
	v_readlane_b32 s69, v2, 5
	v_readlane_b32 s70, v2, 6
	v_readlane_b32 s71, v2, 7
	v_readlane_b32 s72, v2, 8
	v_readlane_b32 s73, v2, 9
	v_readlane_b32 s74, v2, 10
	v_readlane_b32 s75, v2, 11
	v_readlane_b32 s76, v2, 12
	v_readlane_b32 s77, v2, 13
	v_readlane_b32 s78, v2, 14
	v_readlane_b32 s79, v2, 15
	v_readlane_b32 s80, v2, 16
	v_readlane_b32 s81, v2, 17
	v_readlane_b32 s82, v2, 18
	v_readlane_b32 s83, v2, 19
	v_readlane_b32 s84, v2, 20
	v_readlane_b32 s85, v2, 21
	v_readlane_b32 s86, v2, 22
	v_readlane_b32 s87, v2, 23
	v_readlane_b32 s88, v2, 24
	v_readlane_b32 s89, v2, 25
	v_readlane_b32 s90, v2, 26
	v_readlane_b32 s91, v2, 27
	v_readlane_b32 s92, v2, 28
	v_readlane_b32 s93, v2, 29
	v_readlane_b32 s94, v2, 30
	v_readlane_b32 s95, v2, 31
	v_readlane_b32 s96, v2, 32
	v_readlane_b32 s97, v2, 33
	v_mbcnt_lo_u32_b32 v144, -1, 0
	v_mbcnt_hi_u32_b32 v144, -1, v144
	s_nop 7
	s_branch .Ltail_entry
.Lmq_setup:
	s_add_u32 s3, s76, 0x13d40080
	s_addc_u32 s28, s77, 0
	s_add_u32 s29, s76, 0x1600100
	s_addc_u32 s33, s77, 0
	s_add_i32 s48, 0, 0x27e40
	s_mov_b32 s5, 0
	v_mov_b32_e32 v129, 0
	s_movk_i32 s46, 0x200
	s_movk_i32 s47, 0x70
	v_mov_b32_e32 v140, s48
	s_mov_b32 s49, 0x1fffe0
	s_mov_b64 s[6:7], 0x80
	s_mov_b64 s[8:9], 0x100
	v_mov_b32_e32 v141, 1
	s_barrier
	s_branch .LBB0_1201
